# norm row loop: one more mid-batch wait (row 3's scale/shift loads wait for the x loads): fewer loads in flight per wave
# speedup vs baseline: 1.0028x; 1.0028x over previous
.LBB0_759:
	s_lshl_b64 s[26:27], s[26:27], 12
	s_waitcnt lgkmcnt(0)
	s_add_u32 s2, s2, s26
	s_addc_u32 s3, s3, s27
	global_load_dwordx4 v[192:195], v208, s[2:3]
	global_load_dwordx4 v[156:159], v208, s[2:3] offset:1024
	global_load_dwordx4 v[148:151], v208, s[2:3] offset:2048
	global_load_dwordx4 v[144:147], v208, s[2:3] offset:3072
	s_and_b64 vcc, exec, s[0:1]
	s_cbranch_vccnz .LBB0_761
	s_add_i32 s3, s22, 0xffffc000
	s_lshr_b32 s3, s3, 2
	s_ashr_i32 s2, s22, 12
	s_add_i32 s3, s3, 4
	s_cmpk_lt_i32 s22, 0x4000
	s_cselect_b32 s2, s2, s3
	s_mul_hi_i32 s3, s2, 0x6000
	s_mulk_i32 s2, 0x6000
	s_add_u32 s2, s31, s2
	s_addc_u32 s3, s34, s3
	s_waitcnt vmcnt(0)
	v_lshl_add_u64 v[16:17], s[2:3], 0, v[208:209]
	s_mov_b64 s[22:23], 0x1000
	v_add_co_u32_e32 v26, vcc, 0x1000, v16
	v_lshl_add_u64 v[24:25], v[16:17], 0, s[22:23]
	s_nop 0
	v_addc_co_u32_e32 v27, vcc, 0, v17, vcc
	global_load_dwordx4 v[76:79], v208, s[2:3]
	global_load_dwordx4 v[84:87], v208, s[2:3] offset:1024
	global_load_dwordx4 v[20:23], v[24:25], off offset:1024
	global_load_dwordx4 v[16:19], v[24:25], off offset:2048
	global_load_dwordx4 v[28:31], v[26:27], off
	s_nop 0
	global_load_dwordx4 v[24:27], v[24:25], off offset:3072
	s_nop 0
	global_load_dwordx4 v[100:103], v208, s[2:3] offset:2048
	global_load_dwordx4 v[96:99], v208, s[2:3] offset:3072
